# P1: prompt rows dealt over 240 workgroups, last 16 take one 32-row sample batch each (single adaLN staging per workgroup)
# speedup vs baseline: 1.0239x; 1.0036x over previous
.LBB0_85:
	s_or_b64 exec, exec, s[4:5]
	s_abs_i32 s5, s92
	v_cvt_f32_u32_e32 v0, s5
	s_sub_i32 s2, 0, s5
	s_add_i32 s0, s92, 0x21ff
	s_xor_b32 s1, s0, s92
	v_rcp_iflag_f32_e32 v0, v0
	s_abs_i32 s0, s0
	s_ashr_i32 s1, s1, 31
	v_mov_b32_e32 v64, v250
	v_mul_f32_e32 v0, 0x4f7ffffe, v0
	v_cvt_u32_f32_e32 v0, v0
	s_nop 0
	v_readfirstlane_b32 s3, v0
	s_mul_i32 s2, s2, s3
	s_mul_hi_u32 s2, s3, s2
	s_add_i32 s2, s3, s2
	v_writelane_b32 v254, s2, 52
	s_mul_hi_u32 s2, s0, s2
	s_mul_i32 s3, s2, s5
	s_sub_i32 s0, s0, s3
	s_add_i32 s4, s2, 1
	s_sub_i32 s3, s0, s5
	s_cmp_ge_u32 s0, s5
	s_cselect_b32 s2, s4, s2
	s_cselect_b32 s0, s3, s0
	s_add_i32 s3, s2, 1
	s_cmp_ge_u32 s0, s5
	s_cselect_b32 s0, s3, s2
	s_xor_b32 s0, s0, s1
	s_sub_i32 s0, s0, s1
	s_mul_i32 s2, s0, s96
	s_add_i32 s0, s2, s0
	s_min_i32 s24, s0, 0x2200
	s_cmp_lt_i32 s2, s24
	v_writelane_b32 v254, s5, 54
	s_cselect_b64 s[0:1], -1, 0
	v_writelane_b32 v254, s0, 56
	s_cmp_ge_i32 s2, s24
	s_nop 0
	v_writelane_b32 v254, s1, 57
	v_writelane_b32 v254, s2, 58
	v_writelane_b32 v254, s24, 59
	v_writelane_b32 v254, s52, 60
	s_nop 1
	v_writelane_b32 v254, s53, 61
	s_cbranch_scc1 .LBB0_101
	v_max_i32_e32 v1, 0x600, v64
	s_movk_i32 s0, 0x800
	v_sub_u32_e32 v1, v1, v64
	v_cmp_gt_i32_e64 s[4:5], s0, v64
	s_movk_i32 s0, 0x1ff
	v_add_u32_e32 v1, 0x1ff, v1
	v_lshlrev_b32_e32 v83, 2, v64
	v_lshrrev_b32_e32 v3, 9, v1
	v_cmp_lt_u32_e64 s[6:7], s0, v1
	v_and_b32_e32 v1, 63, v64
	v_and_b32_e32 v0, 0xfc, v83
	v_mov_b32_e32 v67, 0
	v_add_u32_e32 v3, 1, v3
	v_lshlrev_b32_e32 v66, 3, v1
	v_lshl_add_u32 v84, v0, 2, 32
	v_or_b32_e32 v2, 0x400, v0
	v_or_b32_e32 v4, 0x500, v0
	v_or_b32_e32 v6, 0x600, v0
	v_or_b32_e32 v8, 0x700, v0
	v_and_b32_e32 v85, 0xfffffe, v3
	v_lshl_add_u64 v[10:11], s[50:51], 0, v[66:67]
	s_mov_b64 s[0:1], 0x495d700
	v_lshlrev_b32_e32 v66, 2, v0
	v_mbcnt_lo_u32_b32 v0, -1, 0
	v_ashrrev_i32_e32 v82, 6, v64
	v_lshl_add_u32 v86, v85, 9, v64
	v_add_u32_e32 v65, 0x200, v64
	v_cmp_ne_u32_e64 s[8:9], v3, v85
	v_add_u32_e32 v87, 32, v83
	v_lshl_add_u64 v[68:69], v[10:11], 0, s[0:1]
	s_mov_b64 s[0:1], 0x2000
	v_lshlrev_b32_e32 v70, 2, v2
	v_lshlrev_b32_e32 v72, 2, v4
	v_lshlrev_b32_e32 v74, 2, v6
	v_lshlrev_b32_e32 v76, 2, v8
	v_mov_b32_e32 v88, 0x358637bd
	v_mbcnt_hi_u32_b32 v89, -1, v0
	v_readlane_b32 s3, v254, 58
	s_cmpk_eq_u32 s92, 0x100
	s_cbranch_scc0 .Lp1_nomap
	s_cmpk_lt_u32 s96, 0xf0
	s_cbranch_scc0 .Lp1_samp
	s_mul_i32 s3, s96, 34
	s_min_u32 s98, s96, 32
	s_add_i32 s3, s3, s98
	s_add_i32 s24, s3, 34
	s_cmpk_lt_u32 s96, 32
	s_addc_u32 s24, s24, 0
	s_branch .Lp1_wr
.Lp1_samp:
	s_sub_i32 s98, s96, 0xf0
	s_lshl_b32 s98, s98, 5
	s_add_i32 s3, s98, 0x2000
	s_add_i32 s24, s3, 32
.Lp1_wr:
	v_writelane_b32 v254, s3, 58
	v_writelane_b32 v254, s24, 59
.Lp1_nomap:
	s_branch .LBB0_88
.LBB0_87:
	s_or_b64 exec, exec, s[12:13]
	s_cmp_ge_i32 s2, s24
	s_mov_b32 s3, s14
	s_cbranch_scc1 .LBB0_101
